# GDN recurrence: packed v_pk_mul_f32 replaced by scalar v_mul_f32 pairs (same arithmetic) beside the MFMAs
# speedup vs baseline: 1.0002x; 1.0002x over previous
; #define LAS __attribute__((address_space(3)))
; #define LDS_WAIT() asm volatile("s_waitcnt lgkmcnt(0)" ::: "memory")
; #define LDS_BARRIER() do { asm volatile("s_waitcnt lgkmcnt(0)" ::: "memory"); __builtin_amdgcn_s_barrier(); asm volatile("" ::: "memory"); } while (0)
; #define MFMA16(a, b, c) __builtin_amdgcn_mfma_f32_16x16x32_bf16((a), (b), (c), 0, 0, 0)
; __device__ __forceinline__ void phase_gdn2(Frame& F, bool ctx_out, bool dry = false) {
;     ...
;                 f32x4 U[4];
; #pragma unroll
;                 for (int I = 0; I < 4; ++I) {
;                     const hb8 fa = *(const LAS hb8*)(TUB + (I * 16 + l15) * GB + q4 * 8), fb = *(const LAS hb8*)(VT + (vb * 16 + l15) * GT + I * 16 + q4 * 8);
;                     U[I] = MFMA16(fa, fb, ((f32x4){0.f, 0.f, 0.f, 0.f}));
;                     const hb8 ga = *(const LAS hb8*)(KCT + (vb * 16 + l15) * GT + I * 16 + q4 * 8), gbv = *(const LAS hb8*)(TWB + (I * 16 + l15) * GB + q4 * 8);
;                     const f32x4 wt = MFMA16(ga, gbv, ((f32x4){0.f, 0.f, 0.f, 0.f}));
;                     *(LAS v2u*)(W + (I * 16 + l15) * GS + vb * 16 + q4 * 4) = (v2u){pk2(-wt.x, -wt.y), pk2(-wt.z, -wt.w)};
;                 }
;                 LDS_WAIT(); asm volatile("" ::: "memory");
;                 LDS_BARRIER();
; #pragma unroll
;                 for (int I = 0; I < 4; ++I) {
;                     f32x4 vn = U[I], oa = (f32x4){0.f, 0.f, 0.f, 0.f};
; #pragma unroll
;                     for (int ks = 0; ks < 4; ++ks) {
;                         const v4u sb4 = (v4u){pk2(S[2 * ks].x, S[2 * ks].y), pk2(S[2 * ks].z, S[2 * ks].w), pk2(S[2 * ks + 1].x, S[2 * ks + 1].y), pk2(S[2 * ks + 1].z, S[2 * ks + 1].w)};
;                         const hb8 fb = __builtin_bit_cast(hb8, sb4);
;                         const v2u w0 = *(const LAS v2u*)(W + (I * 16 + l15) * GS + ks * 32 + q4 * 4), w1 = *(const LAS v2u*)(W + (I * 16 + l15) * GS + ks * 32 + 16 + q4 * 4);
;                         const v2u q0 = *(const LAS v2u*)(QC + (I * 16 + l15) * GS + ks * 32 + q4 * 4), q1 = *(const LAS v2u*)(QC + (I * 16 + l15) * GS + ks * 32 + 16 + q4 * 4);
;                         const v4u fw4 = (v4u){w0.x, w0.y, w1.x, w1.y}, fq4 = (v4u){q0.x, q0.y, q1.x, q1.y};
;                         vn = MFMA16(__builtin_bit_cast(hb8, fw4), fb, vn); oa = MFMA16(__builtin_bit_cast(hb8, fq4), fb, oa); }
.Lgdn_drained:
	v_add3_u32 v88, s0, v0, v1
	ds_read_b128 v[68:71], v88
	ds_read_b128 v[72:75], v3 offset:55296
	s_waitcnt lgkmcnt(0)
	v_mfma_f32_16x16x32_bf16 v[68:71], v[68:71], v[72:75], 0
	ds_read_b128 v[72:75], v3 offset:34816
	v_add3_u32 v89, s47, v0, v1
	ds_read_b128 v[76:79], v89
	s_waitcnt lgkmcnt(0)
	v_mfma_f32_16x16x32_bf16 v[72:75], v[72:75], v[76:79], 0
	v_add_u32_e32 v108, 0, v139
	v_add_u32_e32 v107, s76, v140
	v_add_u32_e32 v101, s85, v139
	s_nop 4
	v_xor_b32_e32 v0, 0x80000000, v73
	v_xor_b32_e32 v1, 0x80000000, v72
	v_cvt_pk_bf16_f32 v0, v1, v0
	v_xor_b32_e32 v1, 0x80000000, v74
	v_xor_b32_e32 v72, 0x80000000, v75
	v_cvt_pk_bf16_f32 v1, v1, v72
	v_mul_u32_u24_e32 v72, 0x110, v137
	v_add3_u32 v92, s67, v139, v72
	ds_write_b64 v92, v[0:1]
	ds_read_b128 v[72:75], v88 offset:1280
	ds_read_b128 v[76:79], v3 offset:55328
	s_waitcnt lgkmcnt(0)
	v_mfma_f32_16x16x32_bf16 v[80:83], v[72:75], v[76:79], 0
	ds_read_b128 v[72:75], v3 offset:34848
	ds_read_b128 v[76:79], v89 offset:1280
	v_mad_u32_u24 v103, v137, s10, v108
	v_or_b32_e32 v110, 16, v137
	s_waitcnt lgkmcnt(0)
	v_mfma_f32_16x16x32_bf16 v[72:75], v[72:75], v[76:79], 0
	v_mad_u32_u24 v104, v110, s10, v108
	v_or_b32_e32 v109, 32, v137
	v_or_b32_e32 v100, 48, v137
	s_nop 4
	v_xor_b32_e32 v0, 0x80000000, v73
	v_xor_b32_e32 v1, 0x80000000, v72
	v_cvt_pk_bf16_f32 v0, v1, v0
	v_xor_b32_e32 v1, 0x80000000, v74
	v_xor_b32_e32 v72, 0x80000000, v75
	v_cvt_pk_bf16_f32 v1, v1, v72
	ds_write_b64 v92, v[0:1] offset:4352
	ds_read_b128 v[72:75], v88 offset:2560
	ds_read_b128 v[76:79], v3 offset:55360
	s_waitcnt lgkmcnt(0)
	v_mfma_f32_16x16x32_bf16 v[76:79], v[72:75], v[76:79], 0
	ds_read_b128 v[72:75], v3 offset:34880
	ds_read_b128 v[84:87], v89 offset:2560
	s_add_i32 s56, s56, 1
	s_add_i32 s3, s3, 64
	s_waitcnt lgkmcnt(0)
	v_mfma_f32_16x16x32_bf16 v[72:75], v[72:75], v[84:87], 0
	s_add_i32 s96, s96, 1
	s_cmpk_eq_i32 s3, 0x900
	s_nop 5
	v_xor_b32_e32 v0, 0x80000000, v73
	v_xor_b32_e32 v1, 0x80000000, v72
	v_cvt_pk_bf16_f32 v0, v1, v0
	v_xor_b32_e32 v1, 0x80000000, v74
	v_xor_b32_e32 v72, 0x80000000, v75
	v_cvt_pk_bf16_f32 v1, v1, v72
	ds_write_b64 v92, v[0:1] offset:8704
	ds_read_b128 v[72:75], v88 offset:3840
	ds_read_b128 v[84:87], v3 offset:55392
	s_waitcnt lgkmcnt(0)
	v_mfma_f32_16x16x32_bf16 v[72:75], v[72:75], v[84:87], 0
	ds_read_b128 v[84:87], v3 offset:34912
	ds_read_b128 v[88:91], v89 offset:3840
	s_waitcnt lgkmcnt(0)
	v_mfma_f32_16x16x32_bf16 v[84:87], v[84:87], v[88:91], 0
	v_cvt_pk_bf16_f32 v88, v40, v41
	v_cvt_pk_bf16_f32 v89, v42, v43
	s_nop 5
	v_xor_b32_e32 v0, 0x80000000, v85
	v_xor_b32_e32 v1, 0x80000000, v84
	v_cvt_pk_bf16_f32 v0, v1, v0
	v_xor_b32_e32 v1, 0x80000000, v86
	v_xor_b32_e32 v3, 0x80000000, v87
	v_cvt_pk_bf16_f32 v1, v1, v3
	ds_write_b64 v92, v[0:1] offset:13056
	v_add_u32_e32 v0, 0, v140
	s_waitcnt lgkmcnt(0)
	v_add_u32_e32 v106, 0x24a80, v0
	v_add_u32_e32 v102, 0x24b80, v0
	v_mul_u32_u24_e32 v0, 0x88, v137
	v_lshl_add_u32 v0, v0, 1, v108
	s_waitcnt lgkmcnt(0)
	s_barrier
	v_mov_b32_e32 v218, 0
	v_mov_b32_e32 v219, 0
	v_mov_b32_e32 v234, 0
	v_mov_b32_e32 v235, 0
	v_mov_b32_e32 v242, 0
	v_mov_b32_e32 v243, 0
	v_mov_b32_e32 v246, 0
	v_mov_b32_e32 v247, 0
	v_mov_b32_e32 v250, s76
	ds_read_b128 v[236:239], v250 offset:768
	ds_read_b64 v[154:155], v0
	ds_read_b64 v[156:157], v0 offset:32
	ds_read_b64 v[170:171], v0 offset:17408
	ds_read_b64 v[172:173], v0 offset:17440
	ds_read_b64 v[158:159], v0 offset:64
	ds_read_b64 v[160:161], v0 offset:96
	ds_read_b64 v[174:175], v0 offset:17472
	ds_read_b64 v[176:177], v0 offset:17504
	v_mad_u32_u24 v252, v137, s84, v101
	v_lshlrev_b32_e32 v92, 1, v137
	v_mul_u32_u24_e32 v93, 0x440, v138
	v_add3_u32 v253, s89, v92, v93
	v_cvt_pk_bf16_f32 v186, v36, v37
	v_cvt_pk_bf16_f32 v187, v38, v39
	v_cvt_pk_bf16_f32 v188, v40, v41
	v_cvt_pk_bf16_f32 v189, v42, v43
	ds_read_b64 v[162:163], v0 offset:128
	ds_read_b64 v[164:165], v0 offset:160
	ds_read_b64 v[178:179], v0 offset:17536
	ds_read_b64 v[180:181], v0 offset:17568
	s_waitcnt lgkmcnt(8)
	v_mfma_f32_16x16x32_bf16 v[68:71], v[154:157], v[186:189], v[68:71]
	v_mfma_f32_16x16x32_bf16 v[84:87], v[170:173], v[186:189], 0
	v_cvt_pk_bf16_f32 v190, v44, v45
	v_cvt_pk_bf16_f32 v191, v46, v47
	v_cvt_pk_bf16_f32 v192, v48, v49
	v_cvt_pk_bf16_f32 v193, v50, v51
	ds_read_b64 v[166:167], v0 offset:192
	ds_read_b64 v[168:169], v0 offset:224
	ds_read_b64 v[182:183], v0 offset:17600
	ds_read_b64 v[184:185], v0 offset:17632
	s_waitcnt lgkmcnt(8)
	v_mfma_f32_16x16x32_bf16 v[68:71], v[158:161], v[190:193], v[68:71]
	v_mfma_f32_16x16x32_bf16 v[84:87], v[174:177], v[190:193], v[84:87]
	v_cvt_pk_bf16_f32 v194, v52, v53
	v_cvt_pk_bf16_f32 v195, v54, v55
	v_cvt_pk_bf16_f32 v196, v56, v57
	v_cvt_pk_bf16_f32 v197, v58, v59
	ds_read_b64 v[202:203], v103 offset:34816
	ds_read_b64 v[204:205], v104 offset:34816
	ds_read_b64 v[206:207], v104 offset:37376
	ds_read_b64 v[208:209], v104 offset:39936
	s_waitcnt lgkmcnt(8)
	v_mfma_f32_16x16x32_bf16 v[68:71], v[162:165], v[194:197], v[68:71]
	v_mfma_f32_16x16x32_bf16 v[84:87], v[178:181], v[194:197], v[84:87]
	v_cvt_pk_bf16_f32 v198, v60, v61
	v_cvt_pk_bf16_f32 v199, v62, v63
	v_cvt_pk_bf16_f32 v200, v64, v65
	v_cvt_pk_bf16_f32 v201, v66, v67
	ds_read_b64 v[210:211], v103 offset:45056
	ds_read_b64 v[212:213], v103 offset:47616
	ds_read_b64 v[214:215], v103 offset:50176
	ds_read_b64 v[216:217], v103 offset:52736
	s_waitcnt lgkmcnt(8)
; #define LAS __attribute__((address_space(3)))
; __device__ __forceinline__ void phase_gdn2(Frame& F, bool ctx_out, bool dry = false) {
;     ...
; #pragma unroll
;                 for (int I = 0; I < 4; ++I) {
;                     f32x4 vn = U[I], oa = (f32x4){0.f, 0.f, 0.f, 0.f};
; #pragma unroll
;                     for (int ks = 0; ks < 4; ++ks) {
;                         const v4u sb4 = (v4u){pk2(S[2 * ks].x, S[2 * ks].y), pk2(S[2 * ks].z, S[2 * ks].w), pk2(S[2 * ks + 1].x, S[2 * ks + 1].y), pk2(S[2 * ks + 1].z, S[2 * ks + 1].w)};
;                         const hb8 fb = __builtin_bit_cast(hb8, sb4);
;                         const v2u w0 = *(const LAS v2u*)(W + (I * 16 + l15) * GS + ks * 32 + q4 * 4), w1 = *(const LAS v2u*)(W + (I * 16 + l15) * GS + ks * 32 + 16 + q4 * 4);
;                         const v2u q0 = *(const LAS v2u*)(QC + (I * 16 + l15) * GS + ks * 32 + q4 * 4), q1 = *(const LAS v2u*)(QC + (I * 16 + l15) * GS + ks * 32 + 16 + q4 * 4);
;                         const v4u fw4 = (v4u){w0.x, w0.y, w1.x, w1.y}, fq4 = (v4u){q0.x, q0.y, q1.x, q1.y};
;                         vn = MFMA16(__builtin_bit_cast(hb8, fw4), fb, vn); oa = MFMA16(__builtin_bit_cast(hb8, fq4), fb, oa); }
;                     const f32x4 ck = *(const LAS f32x4*)(s_ckd + I * 16 + q4 * 4), eg = *(const LAS f32x4*)(s_eG + I * 16 + q4 * 4), rqv = *(const LAS f32x4*)(s_rq + I * 16 + q4 * 4);
;                     const v4u vn4 = (v4u){pk2(vn.x, vn.y), pk2(vn.z, vn.w), 0u, 0u}, vp4 = (v4u){pk2(vn.x * ck.x, vn.y * ck.y), pk2(vn.z * ck.z, vn.w * ck.w), 0u, 0u};
;                     oa = oa * eg;
;                     { const v2u a0 = *(const LAS v2u*)(QKB + (I * 16 + l15) * GB + q4 * 4); const v4u fa4 = (v4u){a0.x, a0.y, 0u, 0u}; oa = MFMA16(__builtin_bit_cast(hb8, fa4), __builtin_bit_cast(hb8, vn4), oa); }
;                     oa = oa * rqv;
; #pragma unroll
;                     for (int i = 0; i < 4; ++i) O16[(I * 16 + q4 * 4 + i) * GS + vb * 16 + l15] = (bf16)f2bf(oa[i]);
;                     const float ege = s_eGend[I];
;                     const hb8 fbn = __builtin_bit_cast(hb8, vp4);
; #pragma unroll
;                     for (int kt = 0; kt < 8; ++kt) { const v2u a0 = *(const LAS v2u*)(KCT + (kt * 16 + l15) * GT + I * 16 + q4 * 4); const v4u fa4 = (v4u){a0.x, a0.y, 0u, 0u}; S[kt] = MFMA16(__builtin_bit_cast(hb8, fa4), fbn, S[kt] * ege); }
;                 }
	v_mfma_f32_16x16x32_bf16 v[68:71], v[166:169], v[198:201], v[68:71]
	v_mfma_f32_16x16x32_bf16 v[84:87], v[182:185], v[198:201], v[84:87]
	ds_read_b128 v[220:223], v106
	ds_read_b128 v[224:227], v107 offset:512
	ds_read_b128 v[228:231], v102
	ds_read_b64 v[232:233], v252
	v_mul_f32_e32 v36, v236, v36
	v_mul_f32_e32 v37, v236, v37
	v_mul_f32_e32 v38, v236, v38
	v_mul_f32_e32 v39, v236, v39
	v_mul_f32_e32 v40, v236, v40
	v_mul_f32_e32 v41, v236, v41
	v_mul_f32_e32 v42, v236, v42
	v_mul_f32_e32 v43, v236, v43
	v_mul_f32_e32 v44, v236, v44
	v_mul_f32_e32 v45, v236, v45
	v_mul_f32_e32 v46, v236, v46
	v_mul_f32_e32 v47, v236, v47
	v_mul_f32_e32 v48, v236, v48
	v_mul_f32_e32 v49, v236, v49
	v_mul_f32_e32 v50, v236, v50
	v_mul_f32_e32 v51, v236, v51
	v_mul_f32_e32 v52, v236, v52
	v_mul_f32_e32 v53, v236, v53
	v_mul_f32_e32 v54, v236, v54
	v_mul_f32_e32 v55, v236, v55
	v_mul_f32_e32 v56, v236, v56
	v_mul_f32_e32 v57, v236, v57
	v_mul_f32_e32 v58, v236, v58
	v_mul_f32_e32 v59, v236, v59
	v_mul_f32_e32 v60, v236, v60
	v_mul_f32_e32 v61, v236, v61
	v_mul_f32_e32 v62, v236, v62
	v_mul_f32_e32 v63, v236, v63
	v_mul_f32_e32 v64, v236, v64
	v_mul_f32_e32 v65, v236, v65
	v_mul_f32_e32 v66, v236, v66
	v_mul_f32_e32 v67, v236, v67
	s_waitcnt lgkmcnt(2)
	v_cvt_pk_bf16_f32 v240, v68, v69
	v_cvt_pk_bf16_f32 v241, v70, v71
	v_mul_f32_e32 v88, v68, v220
	v_mul_f32_e32 v89, v69, v221
	v_mul_f32_e32 v90, v70, v222
	v_mul_f32_e32 v91, v71, v223
	v_cvt_pk_bf16_f32 v244, v88, v89
	v_cvt_pk_bf16_f32 v245, v90, v91
	v_mul_f32_e32 v84, v84, v224
	v_mul_f32_e32 v85, v85, v225
	v_mul_f32_e32 v86, v86, v226
	v_mul_f32_e32 v87, v87, v227
	s_waitcnt lgkmcnt(0)
	v_mfma_f32_16x16x32_bf16 v[36:39], v[202:205], v[244:247], v[36:39]
	v_mfma_f32_16x16x32_bf16 v[40:43], v[204:207], v[244:247], v[40:43]
	v_mfma_f32_16x16x32_bf16 v[84:87], v[232:235], v[240:243], v[84:87]
	v_add_u32_e32 v250, 4352, v0
	v_mfma_f32_16x16x32_bf16 v[44:47], v[206:209], v[244:247], v[44:47]
	v_mfma_f32_16x16x32_bf16 v[48:51], v[208:211], v[244:247], v[48:51]
	v_mfma_f32_16x16x32_bf16 v[52:55], v[210:213], v[244:247], v[52:55]
	v_mfma_f32_16x16x32_bf16 v[56:59], v[212:215], v[244:247], v[56:59]
	v_mfma_f32_16x16x32_bf16 v[60:63], v[214:217], v[244:247], v[60:63]
	v_mfma_f32_16x16x32_bf16 v[64:67], v[216:219], v[244:247], v[64:67]
	ds_read_b64 v[154:155], v250
	ds_read_b64 v[156:157], v250 offset:32
	ds_read_b64 v[170:171], v250 offset:17408
	ds_read_b64 v[172:173], v250 offset:17440
	ds_read_b64 v[158:159], v250 offset:64
	ds_read_b64 v[160:161], v250 offset:96
	ds_read_b64 v[174:175], v250 offset:17472
	ds_read_b64 v[176:177], v250 offset:17504
	v_mul_f32_e32 v84, v84, v228
	v_mul_f32_e32 v85, v85, v229
	v_mul_f32_e32 v86, v86, v230
	v_mul_f32_e32 v87, v87, v231
	v_cvt_pk_bf16_f32 v88, v84, v85
	v_cvt_pk_bf16_f32 v90, v86, v87
	v_lshrrev_b32_e32 v89, 16, v88
	v_lshrrev_b32_e32 v91, 16, v90
	ds_write_b16 v253, v88
	ds_write_b16 v253, v89 offset:272
	ds_write_b16 v253, v90 offset:544
	ds_write_b16 v253, v91 offset:816
	v_cvt_pk_bf16_f32 v186, v36, v37
	v_cvt_pk_bf16_f32 v187, v38, v39
	v_cvt_pk_bf16_f32 v188, v40, v41
	v_cvt_pk_bf16_f32 v189, v42, v43
	s_waitcnt lgkmcnt(8)
	ds_read_b64 v[162:163], v250 offset:128
	ds_read_b64 v[164:165], v250 offset:160
	ds_read_b64 v[178:179], v250 offset:17536
	ds_read_b64 v[180:181], v250 offset:17568
	s_waitcnt lgkmcnt(8)
	v_mfma_f32_16x16x32_bf16 v[80:83], v[154:157], v[186:189], v[80:83]
	v_mfma_f32_16x16x32_bf16 v[84:87], v[170:173], v[186:189], 0
	v_cvt_pk_bf16_f32 v190, v44, v45
	v_cvt_pk_bf16_f32 v191, v46, v47
	v_cvt_pk_bf16_f32 v192, v48, v49
	v_cvt_pk_bf16_f32 v193, v50, v51
	ds_read_b64 v[166:167], v250 offset:192
	ds_read_b64 v[168:169], v250 offset:224
	ds_read_b64 v[182:183], v250 offset:17600
	ds_read_b64 v[184:185], v250 offset:17632
	s_waitcnt lgkmcnt(8)
	v_mfma_f32_16x16x32_bf16 v[80:83], v[158:161], v[190:193], v[80:83]
	v_mfma_f32_16x16x32_bf16 v[84:87], v[174:177], v[190:193], v[84:87]
	v_cvt_pk_bf16_f32 v194, v52, v53
	v_cvt_pk_bf16_f32 v195, v54, v55
	v_cvt_pk_bf16_f32 v196, v56, v57
	v_cvt_pk_bf16_f32 v197, v58, v59
	ds_read_b64 v[202:203], v103 offset:34848
	ds_read_b64 v[204:205], v104 offset:34848
	ds_read_b64 v[206:207], v104 offset:37408
	ds_read_b64 v[208:209], v104 offset:39968
	s_waitcnt lgkmcnt(8)
	v_mfma_f32_16x16x32_bf16 v[80:83], v[162:165], v[194:197], v[80:83]
	v_mfma_f32_16x16x32_bf16 v[84:87], v[178:181], v[194:197], v[84:87]
	v_cvt_pk_bf16_f32 v198, v60, v61
	v_cvt_pk_bf16_f32 v199, v62, v63
	v_cvt_pk_bf16_f32 v200, v64, v65
	v_cvt_pk_bf16_f32 v201, v66, v67
	ds_read_b64 v[210:211], v103 offset:45088
	ds_read_b64 v[212:213], v103 offset:47648
	ds_read_b64 v[214:215], v103 offset:50208
	ds_read_b64 v[216:217], v103 offset:52768
	s_waitcnt lgkmcnt(8)
	v_mfma_f32_16x16x32_bf16 v[80:83], v[166:169], v[198:201], v[80:83]
	v_mfma_f32_16x16x32_bf16 v[84:87], v[182:185], v[198:201], v[84:87]
	ds_read_b128 v[220:223], v106 offset:64
	ds_read_b128 v[224:227], v107 offset:576
	ds_read_b128 v[228:231], v102 offset:64
	ds_read_b64 v[232:233], v252 offset:1280
	v_mul_f32_e32 v36, v237, v36
	v_mul_f32_e32 v37, v237, v37
	v_mul_f32_e32 v38, v237, v38
	v_mul_f32_e32 v39, v237, v39
	v_mul_f32_e32 v40, v237, v40
	v_mul_f32_e32 v41, v237, v41
	v_mul_f32_e32 v42, v237, v42
	v_mul_f32_e32 v43, v237, v43
	v_mul_f32_e32 v44, v237, v44
	v_mul_f32_e32 v45, v237, v45
	v_mul_f32_e32 v46, v237, v46
	v_mul_f32_e32 v47, v237, v47
	v_mul_f32_e32 v48, v237, v48
	v_mul_f32_e32 v49, v237, v49
	v_mul_f32_e32 v50, v237, v50
	v_mul_f32_e32 v51, v237, v51
	v_mul_f32_e32 v52, v237, v52
	v_mul_f32_e32 v53, v237, v53
	v_mul_f32_e32 v54, v237, v54
	v_mul_f32_e32 v55, v237, v55
	v_mul_f32_e32 v56, v237, v56
	v_mul_f32_e32 v57, v237, v57
	v_mul_f32_e32 v58, v237, v58
	v_mul_f32_e32 v59, v237, v59
	v_mul_f32_e32 v60, v237, v60
	v_mul_f32_e32 v61, v237, v61
	v_mul_f32_e32 v62, v237, v62
	v_mul_f32_e32 v63, v237, v63
	v_mul_f32_e32 v64, v237, v64
	v_mul_f32_e32 v65, v237, v65
	v_mul_f32_e32 v66, v237, v66
	v_mul_f32_e32 v67, v237, v67
	s_waitcnt lgkmcnt(2)
; #define LAS __attribute__((address_space(3)))
; __device__ __forceinline__ void phase_gdn2(Frame& F, bool ctx_out, bool dry = false) {
;     ...
; #pragma unroll
;                 for (int I = 0; I < 4; ++I) {
;                     f32x4 vn = U[I], oa = (f32x4){0.f, 0.f, 0.f, 0.f};
; #pragma unroll
;                     for (int ks = 0; ks < 4; ++ks) {
;                         const v4u sb4 = (v4u){pk2(S[2 * ks].x, S[2 * ks].y), pk2(S[2 * ks].z, S[2 * ks].w), pk2(S[2 * ks + 1].x, S[2 * ks + 1].y), pk2(S[2 * ks + 1].z, S[2 * ks + 1].w)};
;                         const hb8 fb = __builtin_bit_cast(hb8, sb4);
;                         const v2u w0 = *(const LAS v2u*)(W + (I * 16 + l15) * GS + ks * 32 + q4 * 4), w1 = *(const LAS v2u*)(W + (I * 16 + l15) * GS + ks * 32 + 16 + q4 * 4);
;                         const v2u q0 = *(const LAS v2u*)(QC + (I * 16 + l15) * GS + ks * 32 + q4 * 4), q1 = *(const LAS v2u*)(QC + (I * 16 + l15) * GS + ks * 32 + 16 + q4 * 4);
;                         const v4u fw4 = (v4u){w0.x, w0.y, w1.x, w1.y}, fq4 = (v4u){q0.x, q0.y, q1.x, q1.y};
;                         vn = MFMA16(__builtin_bit_cast(hb8, fw4), fb, vn); oa = MFMA16(__builtin_bit_cast(hb8, fq4), fb, oa); }
;                     const f32x4 ck = *(const LAS f32x4*)(s_ckd + I * 16 + q4 * 4), eg = *(const LAS f32x4*)(s_eG + I * 16 + q4 * 4), rqv = *(const LAS f32x4*)(s_rq + I * 16 + q4 * 4);
;                     const v4u vn4 = (v4u){pk2(vn.x, vn.y), pk2(vn.z, vn.w), 0u, 0u}, vp4 = (v4u){pk2(vn.x * ck.x, vn.y * ck.y), pk2(vn.z * ck.z, vn.w * ck.w), 0u, 0u};
;                     oa = oa * eg;
;                     { const v2u a0 = *(const LAS v2u*)(QKB + (I * 16 + l15) * GB + q4 * 4); const v4u fa4 = (v4u){a0.x, a0.y, 0u, 0u}; oa = MFMA16(__builtin_bit_cast(hb8, fa4), __builtin_bit_cast(hb8, vn4), oa); }
;                     oa = oa * rqv;
; #pragma unroll
;                     for (int i = 0; i < 4; ++i) O16[(I * 16 + q4 * 4 + i) * GS + vb * 16 + l15] = (bf16)f2bf(oa[i]);
;                     const float ege = s_eGend[I];
;                     const hb8 fbn = __builtin_bit_cast(hb8, vp4);
; #pragma unroll
;                     for (int kt = 0; kt < 8; ++kt) { const v2u a0 = *(const LAS v2u*)(KCT + (kt * 16 + l15) * GT + I * 16 + q4 * 4); const v4u fa4 = (v4u){a0.x, a0.y, 0u, 0u}; S[kt] = MFMA16(__builtin_bit_cast(hb8, fa4), fbn, S[kt] * ege); }
;                 }
	v_cvt_pk_bf16_f32 v240, v80, v81
	v_cvt_pk_bf16_f32 v241, v82, v83
	v_mul_f32_e32 v88, v80, v220
	v_mul_f32_e32 v89, v81, v221
	v_mul_f32_e32 v90, v82, v222
	v_mul_f32_e32 v91, v83, v223
	v_cvt_pk_bf16_f32 v244, v88, v89
	v_cvt_pk_bf16_f32 v245, v90, v91
	v_mul_f32_e32 v84, v84, v224
	v_mul_f32_e32 v85, v85, v225
	v_mul_f32_e32 v86, v86, v226
	v_mul_f32_e32 v87, v87, v227
	s_waitcnt lgkmcnt(0)
	v_mfma_f32_16x16x32_bf16 v[36:39], v[202:205], v[244:247], v[36:39]
	v_mfma_f32_16x16x32_bf16 v[40:43], v[204:207], v[244:247], v[40:43]
	v_mfma_f32_16x16x32_bf16 v[84:87], v[232:235], v[240:243], v[84:87]
	v_add_u32_e32 v250, 8704, v0
	v_mfma_f32_16x16x32_bf16 v[44:47], v[206:209], v[244:247], v[44:47]
	v_mfma_f32_16x16x32_bf16 v[48:51], v[208:211], v[244:247], v[48:51]
	v_mfma_f32_16x16x32_bf16 v[52:55], v[210:213], v[244:247], v[52:55]
	v_mfma_f32_16x16x32_bf16 v[56:59], v[212:215], v[244:247], v[56:59]
	v_mfma_f32_16x16x32_bf16 v[60:63], v[214:217], v[244:247], v[60:63]
	v_mfma_f32_16x16x32_bf16 v[64:67], v[216:219], v[244:247], v[64:67]
	ds_read_b64 v[154:155], v250
	ds_read_b64 v[156:157], v250 offset:32
	ds_read_b64 v[170:171], v250 offset:17408
	ds_read_b64 v[172:173], v250 offset:17440
	ds_read_b64 v[158:159], v250 offset:64
	ds_read_b64 v[160:161], v250 offset:96
	ds_read_b64 v[174:175], v250 offset:17472
	ds_read_b64 v[176:177], v250 offset:17504
	v_mul_f32_e32 v84, v84, v228
	v_mul_f32_e32 v85, v85, v229
	v_mul_f32_e32 v86, v86, v230
	v_mul_f32_e32 v87, v87, v231
	v_cvt_pk_bf16_f32 v88, v84, v85
	v_cvt_pk_bf16_f32 v90, v86, v87
	v_lshrrev_b32_e32 v89, 16, v88
	v_lshrrev_b32_e32 v91, 16, v90
	ds_write_b16 v253, v88 offset:4352
	ds_write_b16 v253, v89 offset:4624
	ds_write_b16 v253, v90 offset:4896
	ds_write_b16 v253, v91 offset:5168
	v_cvt_pk_bf16_f32 v186, v36, v37
	v_cvt_pk_bf16_f32 v187, v38, v39
	v_cvt_pk_bf16_f32 v188, v40, v41
	v_cvt_pk_bf16_f32 v189, v42, v43
	s_waitcnt lgkmcnt(8)
	ds_read_b64 v[162:163], v250 offset:128
	ds_read_b64 v[164:165], v250 offset:160
	ds_read_b64 v[178:179], v250 offset:17536
	ds_read_b64 v[180:181], v250 offset:17568
	s_waitcnt lgkmcnt(8)
	v_mfma_f32_16x16x32_bf16 v[76:79], v[154:157], v[186:189], v[76:79]
	v_mfma_f32_16x16x32_bf16 v[84:87], v[170:173], v[186:189], 0
	v_cvt_pk_bf16_f32 v190, v44, v45
	v_cvt_pk_bf16_f32 v191, v46, v47
	v_cvt_pk_bf16_f32 v192, v48, v49
	v_cvt_pk_bf16_f32 v193, v50, v51
	ds_read_b64 v[166:167], v250 offset:192
	ds_read_b64 v[168:169], v250 offset:224
	ds_read_b64 v[182:183], v250 offset:17600
	ds_read_b64 v[184:185], v250 offset:17632
	s_waitcnt lgkmcnt(8)
	v_mfma_f32_16x16x32_bf16 v[76:79], v[158:161], v[190:193], v[76:79]
	v_mfma_f32_16x16x32_bf16 v[84:87], v[174:177], v[190:193], v[84:87]
	v_cvt_pk_bf16_f32 v194, v52, v53
	v_cvt_pk_bf16_f32 v195, v54, v55
	v_cvt_pk_bf16_f32 v196, v56, v57
	v_cvt_pk_bf16_f32 v197, v58, v59
	ds_read_b64 v[202:203], v103 offset:34880
	ds_read_b64 v[204:205], v104 offset:34880
	ds_read_b64 v[206:207], v104 offset:37440
	ds_read_b64 v[208:209], v104 offset:40000
	s_waitcnt lgkmcnt(8)
	v_mfma_f32_16x16x32_bf16 v[76:79], v[162:165], v[194:197], v[76:79]
	v_mfma_f32_16x16x32_bf16 v[84:87], v[178:181], v[194:197], v[84:87]
	v_cvt_pk_bf16_f32 v198, v60, v61
	v_cvt_pk_bf16_f32 v199, v62, v63
	v_cvt_pk_bf16_f32 v200, v64, v65
	v_cvt_pk_bf16_f32 v201, v66, v67
	ds_read_b64 v[210:211], v103 offset:45120
	ds_read_b64 v[212:213], v103 offset:47680
	ds_read_b64 v[214:215], v103 offset:50240
	ds_read_b64 v[216:217], v103 offset:52800
	s_waitcnt lgkmcnt(8)
	v_mfma_f32_16x16x32_bf16 v[76:79], v[166:169], v[198:201], v[76:79]
	v_mfma_f32_16x16x32_bf16 v[84:87], v[182:185], v[198:201], v[84:87]
	ds_read_b128 v[220:223], v106 offset:128
	ds_read_b128 v[224:227], v107 offset:640
	ds_read_b128 v[228:231], v102 offset:128
	ds_read_b64 v[232:233], v252 offset:2560
	v_mul_f32_e32 v36, v238, v36
	v_mul_f32_e32 v37, v238, v37
	v_mul_f32_e32 v38, v238, v38
	v_mul_f32_e32 v39, v238, v39
	v_mul_f32_e32 v40, v238, v40
	v_mul_f32_e32 v41, v238, v41
	v_mul_f32_e32 v42, v238, v42
	v_mul_f32_e32 v43, v238, v43
	v_mul_f32_e32 v44, v238, v44
	v_mul_f32_e32 v45, v238, v45
	v_mul_f32_e32 v46, v238, v46
	v_mul_f32_e32 v47, v238, v47
	v_mul_f32_e32 v48, v238, v48
	v_mul_f32_e32 v49, v238, v49
	v_mul_f32_e32 v50, v238, v50
	v_mul_f32_e32 v51, v238, v51
	v_mul_f32_e32 v52, v238, v52
	v_mul_f32_e32 v53, v238, v53
	v_mul_f32_e32 v54, v238, v54
	v_mul_f32_e32 v55, v238, v55
	v_mul_f32_e32 v56, v238, v56
	v_mul_f32_e32 v57, v238, v57
	v_mul_f32_e32 v58, v238, v58
	v_mul_f32_e32 v59, v238, v59
	v_mul_f32_e32 v60, v238, v60
	v_mul_f32_e32 v61, v238, v61
	v_mul_f32_e32 v62, v238, v62
	v_mul_f32_e32 v63, v238, v63
	v_mul_f32_e32 v64, v238, v64
	v_mul_f32_e32 v65, v238, v65
	v_mul_f32_e32 v66, v238, v66
	v_mul_f32_e32 v67, v238, v67
	s_waitcnt lgkmcnt(2)
	v_cvt_pk_bf16_f32 v240, v76, v77
	v_cvt_pk_bf16_f32 v241, v78, v79
	v_mul_f32_e32 v88, v76, v220
	v_mul_f32_e32 v89, v77, v221
	v_mul_f32_e32 v90, v78, v222
	v_mul_f32_e32 v91, v79, v223
	v_cvt_pk_bf16_f32 v244, v88, v89
	v_cvt_pk_bf16_f32 v245, v90, v91
	v_mul_f32_e32 v84, v84, v224
	v_mul_f32_e32 v85, v85, v225
	v_mul_f32_e32 v86, v86, v226
	v_mul_f32_e32 v87, v87, v227
	s_waitcnt lgkmcnt(0)
; #define LAS __attribute__((address_space(3)))
; __device__ __forceinline__ void phase_gdn2(Frame& F, bool ctx_out, bool dry = false) {
;     ...
;                 for (int I = 0; I < 4; ++I) {
;                     f32x4 vn = U[I], oa = (f32x4){0.f, 0.f, 0.f, 0.f};
; #pragma unroll
;                     for (int ks = 0; ks < 4; ++ks) {
;                         const v4u sb4 = (v4u){pk2(S[2 * ks].x, S[2 * ks].y), pk2(S[2 * ks].z, S[2 * ks].w), pk2(S[2 * ks + 1].x, S[2 * ks + 1].y), pk2(S[2 * ks + 1].z, S[2 * ks + 1].w)};
;                         const hb8 fb = __builtin_bit_cast(hb8, sb4);
;                         const v2u w0 = *(const LAS v2u*)(W + (I * 16 + l15) * GS + ks * 32 + q4 * 4), w1 = *(const LAS v2u*)(W + (I * 16 + l15) * GS + ks * 32 + 16 + q4 * 4);
;                         const v2u q0 = *(const LAS v2u*)(QC + (I * 16 + l15) * GS + ks * 32 + q4 * 4), q1 = *(const LAS v2u*)(QC + (I * 16 + l15) * GS + ks * 32 + 16 + q4 * 4);
;                         const v4u fw4 = (v4u){w0.x, w0.y, w1.x, w1.y}, fq4 = (v4u){q0.x, q0.y, q1.x, q1.y};
;                         vn = MFMA16(__builtin_bit_cast(hb8, fw4), fb, vn); oa = MFMA16(__builtin_bit_cast(hb8, fq4), fb, oa); }
;                     const f32x4 ck = *(const LAS f32x4*)(s_ckd + I * 16 + q4 * 4), eg = *(const LAS f32x4*)(s_eG + I * 16 + q4 * 4), rqv = *(const LAS f32x4*)(s_rq + I * 16 + q4 * 4);
;                     const v4u vn4 = (v4u){pk2(vn.x, vn.y), pk2(vn.z, vn.w), 0u, 0u}, vp4 = (v4u){pk2(vn.x * ck.x, vn.y * ck.y), pk2(vn.z * ck.z, vn.w * ck.w), 0u, 0u};
;                     oa = oa * eg;
;                     { const v2u a0 = *(const LAS v2u*)(QKB + (I * 16 + l15) * GB + q4 * 4); const v4u fa4 = (v4u){a0.x, a0.y, 0u, 0u}; oa = MFMA16(__builtin_bit_cast(hb8, fa4), __builtin_bit_cast(hb8, vn4), oa); }
;                     oa = oa * rqv;
; #pragma unroll
;                     for (int i = 0; i < 4; ++i) O16[(I * 16 + q4 * 4 + i) * GS + vb * 16 + l15] = (bf16)f2bf(oa[i]);
;                     const float ege = s_eGend[I];
;                     const hb8 fbn = __builtin_bit_cast(hb8, vp4);
; #pragma unroll
;                     for (int kt = 0; kt < 8; ++kt) { const v2u a0 = *(const LAS v2u*)(KCT + (kt * 16 + l15) * GT + I * 16 + q4 * 4); const v4u fa4 = (v4u){a0.x, a0.y, 0u, 0u}; S[kt] = MFMA16(__builtin_bit_cast(hb8, fa4), fbn, S[kt] * ege); }
;                 }
	v_mfma_f32_16x16x32_bf16 v[36:39], v[202:205], v[244:247], v[36:39]
	v_mfma_f32_16x16x32_bf16 v[40:43], v[204:207], v[244:247], v[40:43]
	v_mfma_f32_16x16x32_bf16 v[84:87], v[232:235], v[240:243], v[84:87]
	v_add_u32_e32 v250, 13056, v0
	v_mfma_f32_16x16x32_bf16 v[44:47], v[206:209], v[244:247], v[44:47]
	v_mfma_f32_16x16x32_bf16 v[48:51], v[208:211], v[244:247], v[48:51]
	v_mfma_f32_16x16x32_bf16 v[52:55], v[210:213], v[244:247], v[52:55]
	v_mfma_f32_16x16x32_bf16 v[56:59], v[212:215], v[244:247], v[56:59]
	v_mfma_f32_16x16x32_bf16 v[60:63], v[214:217], v[244:247], v[60:63]
	v_mfma_f32_16x16x32_bf16 v[64:67], v[216:219], v[244:247], v[64:67]
	ds_read_b64 v[154:155], v250
	ds_read_b64 v[156:157], v250 offset:32
	ds_read_b64 v[170:171], v250 offset:17408
	ds_read_b64 v[172:173], v250 offset:17440
	ds_read_b64 v[158:159], v250 offset:64
	ds_read_b64 v[160:161], v250 offset:96
	ds_read_b64 v[174:175], v250 offset:17472
	ds_read_b64 v[176:177], v250 offset:17504
	v_mul_f32_e32 v84, v84, v228
	v_mul_f32_e32 v85, v85, v229
	v_mul_f32_e32 v86, v86, v230
	v_mul_f32_e32 v87, v87, v231
	v_cvt_pk_bf16_f32 v88, v84, v85
	v_cvt_pk_bf16_f32 v90, v86, v87
	v_lshrrev_b32_e32 v89, 16, v88
	v_lshrrev_b32_e32 v91, 16, v90
	ds_write_b16 v253, v88 offset:8704
	ds_write_b16 v253, v89 offset:8976
	ds_write_b16 v253, v90 offset:9248
	ds_write_b16 v253, v91 offset:9520
	v_cvt_pk_bf16_f32 v186, v36, v37
	v_cvt_pk_bf16_f32 v187, v38, v39
	v_cvt_pk_bf16_f32 v188, v40, v41
	v_cvt_pk_bf16_f32 v189, v42, v43
	s_waitcnt lgkmcnt(8)
	ds_read_b64 v[162:163], v250 offset:128
	ds_read_b64 v[164:165], v250 offset:160
	ds_read_b64 v[178:179], v250 offset:17536
	ds_read_b64 v[180:181], v250 offset:17568
	s_waitcnt lgkmcnt(8)
	v_mfma_f32_16x16x32_bf16 v[72:75], v[154:157], v[186:189], v[72:75]
	v_mfma_f32_16x16x32_bf16 v[84:87], v[170:173], v[186:189], 0
	v_cvt_pk_bf16_f32 v190, v44, v45
	v_cvt_pk_bf16_f32 v191, v46, v47
	v_cvt_pk_bf16_f32 v192, v48, v49
	v_cvt_pk_bf16_f32 v193, v50, v51
	ds_read_b64 v[166:167], v250 offset:192
	ds_read_b64 v[168:169], v250 offset:224
	ds_read_b64 v[182:183], v250 offset:17600
	ds_read_b64 v[184:185], v250 offset:17632
	s_waitcnt lgkmcnt(8)
	v_mfma_f32_16x16x32_bf16 v[72:75], v[158:161], v[190:193], v[72:75]
	v_mfma_f32_16x16x32_bf16 v[84:87], v[174:177], v[190:193], v[84:87]
	v_cvt_pk_bf16_f32 v194, v52, v53
	v_cvt_pk_bf16_f32 v195, v54, v55
	v_cvt_pk_bf16_f32 v196, v56, v57
	v_cvt_pk_bf16_f32 v197, v58, v59
	ds_read_b64 v[202:203], v103 offset:34912
	ds_read_b64 v[204:205], v104 offset:34912
	ds_read_b64 v[206:207], v104 offset:37472
	ds_read_b64 v[208:209], v104 offset:40032
	s_waitcnt lgkmcnt(8)
	v_mfma_f32_16x16x32_bf16 v[72:75], v[162:165], v[194:197], v[72:75]
	v_mfma_f32_16x16x32_bf16 v[84:87], v[178:181], v[194:197], v[84:87]
	v_cvt_pk_bf16_f32 v198, v60, v61
	v_cvt_pk_bf16_f32 v199, v62, v63
	v_cvt_pk_bf16_f32 v200, v64, v65
	v_cvt_pk_bf16_f32 v201, v66, v67
	ds_read_b64 v[210:211], v103 offset:45152
	ds_read_b64 v[212:213], v103 offset:47712
	ds_read_b64 v[214:215], v103 offset:50272
	ds_read_b64 v[216:217], v103 offset:52832
	s_waitcnt lgkmcnt(8)
	v_mfma_f32_16x16x32_bf16 v[72:75], v[166:169], v[198:201], v[72:75]
	v_mfma_f32_16x16x32_bf16 v[84:87], v[182:185], v[198:201], v[84:87]
	ds_read_b128 v[220:223], v106 offset:192
	ds_read_b128 v[224:227], v107 offset:704
	ds_read_b128 v[228:231], v102 offset:192
	ds_read_b64 v[232:233], v252 offset:3840
	v_mul_f32_e32 v36, v239, v36
	v_mul_f32_e32 v37, v239, v37
	v_mul_f32_e32 v38, v239, v38
	v_mul_f32_e32 v39, v239, v39
	v_mul_f32_e32 v40, v239, v40
	v_mul_f32_e32 v41, v239, v41
	v_mul_f32_e32 v42, v239, v42
	v_mul_f32_e32 v43, v239, v43
	v_mul_f32_e32 v44, v239, v44
	v_mul_f32_e32 v45, v239, v45
	v_mul_f32_e32 v46, v239, v46
	v_mul_f32_e32 v47, v239, v47
	v_mul_f32_e32 v48, v239, v48
	v_mul_f32_e32 v49, v239, v49
	v_mul_f32_e32 v50, v239, v50
	v_mul_f32_e32 v51, v239, v51
	v_mul_f32_e32 v52, v239, v52
	v_mul_f32_e32 v53, v239, v53
	v_mul_f32_e32 v54, v239, v54
	v_mul_f32_e32 v55, v239, v55
	v_mul_f32_e32 v56, v239, v56
	v_mul_f32_e32 v57, v239, v57
	v_mul_f32_e32 v58, v239, v58
	v_mul_f32_e32 v59, v239, v59
	v_mul_f32_e32 v60, v239, v60
	v_mul_f32_e32 v61, v239, v61
	v_mul_f32_e32 v62, v239, v62
	v_mul_f32_e32 v63, v239, v63
	v_mul_f32_e32 v64, v239, v64
	v_mul_f32_e32 v65, v239, v65
	v_mul_f32_e32 v66, v239, v66
	v_mul_f32_e32 v67, v239, v67
	s_waitcnt lgkmcnt(2)
	v_cvt_pk_bf16_f32 v240, v72, v73
	v_cvt_pk_bf16_f32 v241, v74, v75
	v_mul_f32_e32 v88, v72, v220
	v_mul_f32_e32 v89, v73, v221
	v_mul_f32_e32 v90, v74, v222
	v_mul_f32_e32 v91, v75, v223
	v_cvt_pk_bf16_f32 v244, v88, v89
	v_cvt_pk_bf16_f32 v245, v90, v91
	v_mul_f32_e32 v84, v84, v224
	v_mul_f32_e32 v85, v85, v225
	v_mul_f32_e32 v86, v86, v226
	v_mul_f32_e32 v87, v87, v227
	s_waitcnt lgkmcnt(0)
	v_mfma_f32_16x16x32_bf16 v[36:39], v[202:205], v[244:247], v[36:39]
	v_mfma_f32_16x16x32_bf16 v[40:43], v[204:207], v[244:247], v[40:43]
	v_mfma_f32_16x16x32_bf16 v[84:87], v[232:235], v[240:243], v[84:87]
	v_mfma_f32_16x16x32_bf16 v[44:47], v[206:209], v[244:247], v[44:47]
	v_mfma_f32_16x16x32_bf16 v[48:51], v[208:211], v[244:247], v[48:51]
	v_mfma_f32_16x16x32_bf16 v[52:55], v[210:213], v[244:247], v[52:55]
	v_mfma_f32_16x16x32_bf16 v[56:59], v[212:215], v[244:247], v[56:59]
	v_mfma_f32_16x16x32_bf16 v[60:63], v[214:217], v[244:247], v[60:63]
	v_mfma_f32_16x16x32_bf16 v[64:67], v[216:219], v[244:247], v[64:67]
	s_nop 1
	v_mul_f32_e32 v84, v84, v228
	v_mul_f32_e32 v85, v85, v229
	v_mul_f32_e32 v86, v86, v230
	v_mul_f32_e32 v87, v87, v231
	v_cvt_pk_bf16_f32 v88, v84, v85
	v_cvt_pk_bf16_f32 v90, v86, v87
	v_lshrrev_b32_e32 v89, 16, v88
	v_lshrrev_b32_e32 v91, 16, v90
	ds_write_b16 v253, v88 offset:13056
	ds_write_b16 v253, v89 offset:13328
	ds_write_b16 v253, v90 offset:13600
	ds_write_b16 v253, v91 offset:13872
	s_waitcnt lgkmcnt(0)
	s_barrier
	s_waitcnt lgkmcnt(0)
	s_cbranch_scc1 .LBB0_1021
